# S5 row-scale table built wave-cooperatively (coalesced 4 rows per load, DPP row reduction); duplicate K-loop LDS waits dropped; S5 cut 44->41
# speedup vs baseline: 1.0229x; 1.0045x over previous
.LBB0_107:
	s_ashr_i32 s70, s34, 6
	s_and_b32 s30, s34, 32
	s_cmp_eq_u32 s30, 0
	s_cselect_b64 s[76:77], -1, 0
	s_cmp_lg_u32 s30, 0
	s_cselect_b64 s[72:73], -1, 0
	s_andn2_b64 vcc, exec, s[74:75]
	s_cbranch_vccnz .LBB0_112
	s_and_b64 s[42:43], s[76:77], exec
	s_cselect_b32 s30, 2, 3
	s_mul_i32 s39, s70, 0x81000
	s_add_u32 s42, s18, s39
	s_addc_u32 s43, s19, 0
	s_sub_u32 s42, s42, 0xf0
	s_subb_u32 s43, s43, 0
	s_mov_b32 s80, 0x10001
	s_mov_b32 s81, 0x10001
	v_lshrrev_b32_e32 v0, 4, v116
	v_lshl_add_u32 v0, s36, 2, v0
	v_and_b32_e32 v1, 15, v116
	v_lshlrev_b32_e32 v2, 8, v0
	v_lshl_add_u32 v2, v1, 4, v2
	v_lshlrev_b32_e32 v3, 2, v0
.Lrq_batch:
	global_load_dwordx4 v[8:11], v2, s[42:43]
	v_add_u32_e32 v4, 0x2000, v2
	global_load_dwordx4 v[12:15], v4, s[42:43]
	v_add_u32_e32 v4, 0x4000, v2
	global_load_dwordx4 v[16:19], v4, s[42:43]
	v_add_u32_e32 v4, 0x6000, v2
	global_load_dwordx4 v[20:23], v4, s[42:43]
	v_add_u32_e32 v4, 0x8000, v2
	global_load_dwordx4 v[24:27], v4, s[42:43]
	v_add_u32_e32 v4, 0xa000, v2
	global_load_dwordx4 v[28:31], v4, s[42:43]
	v_add_u32_e32 v4, 0xc000, v2
	global_load_dwordx4 v[32:35], v4, s[42:43]
	v_add_u32_e32 v4, 0xe000, v2
	global_load_dwordx4 v[36:39], v4, s[42:43]
	v_add_u32_e32 v4, 0x10000, v2
	global_load_dwordx4 v[40:43], v4, s[42:43]
	v_add_u32_e32 v4, 0x12000, v2
	global_load_dwordx4 v[44:47], v4, s[42:43]
	v_add_u32_e32 v4, 0x14000, v2
	global_load_dwordx4 v[48:51], v4, s[42:43]
	v_add_u32_e32 v4, 0x16000, v2
	global_load_dwordx4 v[52:55], v4, s[42:43]
	v_add_u32_e32 v4, 0x18000, v2
	global_load_dwordx4 v[56:59], v4, s[42:43]
	v_add_u32_e32 v4, 0x1a000, v2
	global_load_dwordx4 v[60:63], v4, s[42:43]
	v_add_u32_e32 v4, 0x1c000, v2
	global_load_dwordx4 v[64:67], v4, s[42:43]
	v_add_u32_e32 v4, 0x1e000, v2
	global_load_dwordx4 v[68:71], v4, s[42:43]
	v_add_u32_e32 v4, 0x20000, v2
	global_load_dwordx4 v[72:75], v4, s[42:43]
	v_add_u32_e32 v4, 0x22000, v2
	global_load_dwordx4 v[76:79], v4, s[42:43]
	v_add_u32_e32 v4, 0x24000, v2
	global_load_dwordx4 v[80:83], v4, s[42:43]
	v_add_u32_e32 v4, 0x26000, v2
	global_load_dwordx4 v[84:87], v4, s[42:43]
	v_add_u32_e32 v4, 0x28000, v2
	global_load_dwordx4 v[88:91], v4, s[42:43]
	v_add_u32_e32 v4, 0x2a000, v2
	global_load_dwordx4 v[92:95], v4, s[42:43]
	v_add_u32_e32 v2, 0x2c000, v2
	s_waitcnt vmcnt(21)
	v_add_f32_e32 v8, v8, v9
	v_add_f32_e32 v10, v10, v11
	v_add_f32_e32 v8, v8, v10
	s_waitcnt vmcnt(20)
	v_add_f32_e32 v12, v12, v13
	v_add_f32_e32 v14, v14, v15
	v_add_f32_e32 v12, v12, v14
	s_waitcnt vmcnt(19)
	v_add_f32_e32 v16, v16, v17
	v_add_f32_e32 v18, v18, v19
	v_add_f32_e32 v16, v16, v18
	s_waitcnt vmcnt(18)
	v_add_f32_e32 v20, v20, v21
	v_add_f32_e32 v22, v22, v23
	v_add_f32_e32 v20, v20, v22
	s_waitcnt vmcnt(17)
	v_add_f32_e32 v24, v24, v25
	v_add_f32_e32 v26, v26, v27
	v_add_f32_e32 v24, v24, v26
	s_waitcnt vmcnt(16)
	v_add_f32_e32 v28, v28, v29
	v_add_f32_e32 v30, v30, v31
	v_add_f32_e32 v28, v28, v30
	s_waitcnt vmcnt(15)
	v_add_f32_e32 v32, v32, v33
	v_add_f32_e32 v34, v34, v35
	v_add_f32_e32 v32, v32, v34
	s_waitcnt vmcnt(14)
	v_add_f32_e32 v36, v36, v37
	v_add_f32_e32 v38, v38, v39
	v_add_f32_e32 v36, v36, v38
	s_waitcnt vmcnt(13)
	v_add_f32_e32 v40, v40, v41
	v_add_f32_e32 v42, v42, v43
	v_add_f32_e32 v40, v40, v42
	s_waitcnt vmcnt(12)
	v_add_f32_e32 v44, v44, v45
	v_add_f32_e32 v46, v46, v47
	v_add_f32_e32 v44, v44, v46
	s_waitcnt vmcnt(11)
	v_add_f32_e32 v48, v48, v49
	v_add_f32_e32 v50, v50, v51
	v_add_f32_e32 v48, v48, v50
	s_waitcnt vmcnt(10)
	v_add_f32_e32 v52, v52, v53
	v_add_f32_e32 v54, v54, v55
	v_add_f32_e32 v52, v52, v54
	s_waitcnt vmcnt(9)
	v_add_f32_e32 v56, v56, v57
	v_add_f32_e32 v58, v58, v59
	v_add_f32_e32 v56, v56, v58
	s_waitcnt vmcnt(8)
	v_add_f32_e32 v60, v60, v61
	v_add_f32_e32 v62, v62, v63
	v_add_f32_e32 v60, v60, v62
	s_waitcnt vmcnt(7)
	v_add_f32_e32 v64, v64, v65
	v_add_f32_e32 v66, v66, v67
	v_add_f32_e32 v64, v64, v66
	s_waitcnt vmcnt(6)
	v_add_f32_e32 v68, v68, v69
	v_add_f32_e32 v70, v70, v71
	v_add_f32_e32 v68, v68, v70
	s_waitcnt vmcnt(5)
	v_add_f32_e32 v72, v72, v73
	v_add_f32_e32 v74, v74, v75
	v_add_f32_e32 v72, v72, v74
	s_waitcnt vmcnt(4)
	v_add_f32_e32 v76, v76, v77
	v_add_f32_e32 v78, v78, v79
	v_add_f32_e32 v76, v76, v78
	s_waitcnt vmcnt(3)
	v_add_f32_e32 v80, v80, v81
	v_add_f32_e32 v82, v82, v83
	v_add_f32_e32 v80, v80, v82
	s_waitcnt vmcnt(2)
	v_add_f32_e32 v84, v84, v85
	v_add_f32_e32 v86, v86, v87
	v_add_f32_e32 v84, v84, v86
	s_waitcnt vmcnt(1)
	v_add_f32_e32 v88, v88, v89
	v_add_f32_e32 v90, v90, v91
	v_add_f32_e32 v88, v88, v90
	s_waitcnt vmcnt(0)
	v_add_f32_e32 v92, v92, v93
	v_add_f32_e32 v94, v94, v95
	v_add_f32_e32 v92, v92, v94
	v_add_f32_dpp v9, v8, v8 quad_perm:[1,0,3,2] row_mask:0xf bank_mask:0xf
	v_add_f32_dpp v13, v12, v12 quad_perm:[1,0,3,2] row_mask:0xf bank_mask:0xf
	v_add_f32_dpp v17, v16, v16 quad_perm:[1,0,3,2] row_mask:0xf bank_mask:0xf
	v_add_f32_dpp v21, v20, v20 quad_perm:[1,0,3,2] row_mask:0xf bank_mask:0xf
	v_add_f32_dpp v25, v24, v24 quad_perm:[1,0,3,2] row_mask:0xf bank_mask:0xf
	v_add_f32_dpp v29, v28, v28 quad_perm:[1,0,3,2] row_mask:0xf bank_mask:0xf
	v_add_f32_dpp v33, v32, v32 quad_perm:[1,0,3,2] row_mask:0xf bank_mask:0xf
	v_add_f32_dpp v37, v36, v36 quad_perm:[1,0,3,2] row_mask:0xf bank_mask:0xf
	v_add_f32_dpp v41, v40, v40 quad_perm:[1,0,3,2] row_mask:0xf bank_mask:0xf
	v_add_f32_dpp v45, v44, v44 quad_perm:[1,0,3,2] row_mask:0xf bank_mask:0xf
	v_add_f32_dpp v49, v48, v48 quad_perm:[1,0,3,2] row_mask:0xf bank_mask:0xf
	v_add_f32_dpp v53, v52, v52 quad_perm:[1,0,3,2] row_mask:0xf bank_mask:0xf
	v_add_f32_dpp v57, v56, v56 quad_perm:[1,0,3,2] row_mask:0xf bank_mask:0xf
	v_add_f32_dpp v61, v60, v60 quad_perm:[1,0,3,2] row_mask:0xf bank_mask:0xf
	v_add_f32_dpp v65, v64, v64 quad_perm:[1,0,3,2] row_mask:0xf bank_mask:0xf
	v_add_f32_dpp v69, v68, v68 quad_perm:[1,0,3,2] row_mask:0xf bank_mask:0xf
	v_add_f32_dpp v73, v72, v72 quad_perm:[1,0,3,2] row_mask:0xf bank_mask:0xf
	v_add_f32_dpp v77, v76, v76 quad_perm:[1,0,3,2] row_mask:0xf bank_mask:0xf
	v_add_f32_dpp v81, v80, v80 quad_perm:[1,0,3,2] row_mask:0xf bank_mask:0xf
	v_add_f32_dpp v85, v84, v84 quad_perm:[1,0,3,2] row_mask:0xf bank_mask:0xf
	v_add_f32_dpp v89, v88, v88 quad_perm:[1,0,3,2] row_mask:0xf bank_mask:0xf
	v_add_f32_dpp v93, v92, v92 quad_perm:[1,0,3,2] row_mask:0xf bank_mask:0xf
	v_add_f32_dpp v8, v9, v9 quad_perm:[2,3,0,1] row_mask:0xf bank_mask:0xf
	v_add_f32_dpp v12, v13, v13 quad_perm:[2,3,0,1] row_mask:0xf bank_mask:0xf
	v_add_f32_dpp v16, v17, v17 quad_perm:[2,3,0,1] row_mask:0xf bank_mask:0xf
	v_add_f32_dpp v20, v21, v21 quad_perm:[2,3,0,1] row_mask:0xf bank_mask:0xf
	v_add_f32_dpp v24, v25, v25 quad_perm:[2,3,0,1] row_mask:0xf bank_mask:0xf
	v_add_f32_dpp v28, v29, v29 quad_perm:[2,3,0,1] row_mask:0xf bank_mask:0xf
	v_add_f32_dpp v32, v33, v33 quad_perm:[2,3,0,1] row_mask:0xf bank_mask:0xf
	v_add_f32_dpp v36, v37, v37 quad_perm:[2,3,0,1] row_mask:0xf bank_mask:0xf
	v_add_f32_dpp v40, v41, v41 quad_perm:[2,3,0,1] row_mask:0xf bank_mask:0xf
	v_add_f32_dpp v44, v45, v45 quad_perm:[2,3,0,1] row_mask:0xf bank_mask:0xf
	v_add_f32_dpp v48, v49, v49 quad_perm:[2,3,0,1] row_mask:0xf bank_mask:0xf
	v_add_f32_dpp v52, v53, v53 quad_perm:[2,3,0,1] row_mask:0xf bank_mask:0xf
	v_add_f32_dpp v56, v57, v57 quad_perm:[2,3,0,1] row_mask:0xf bank_mask:0xf
	v_add_f32_dpp v60, v61, v61 quad_perm:[2,3,0,1] row_mask:0xf bank_mask:0xf
	v_add_f32_dpp v64, v65, v65 quad_perm:[2,3,0,1] row_mask:0xf bank_mask:0xf
	v_add_f32_dpp v68, v69, v69 quad_perm:[2,3,0,1] row_mask:0xf bank_mask:0xf
	v_add_f32_dpp v72, v73, v73 quad_perm:[2,3,0,1] row_mask:0xf bank_mask:0xf
	v_add_f32_dpp v76, v77, v77 quad_perm:[2,3,0,1] row_mask:0xf bank_mask:0xf
	v_add_f32_dpp v80, v81, v81 quad_perm:[2,3,0,1] row_mask:0xf bank_mask:0xf
	v_add_f32_dpp v84, v85, v85 quad_perm:[2,3,0,1] row_mask:0xf bank_mask:0xf
	v_add_f32_dpp v88, v89, v89 quad_perm:[2,3,0,1] row_mask:0xf bank_mask:0xf
	v_add_f32_dpp v92, v93, v93 quad_perm:[2,3,0,1] row_mask:0xf bank_mask:0xf
	v_add_f32_dpp v9, v8, v8 row_half_mirror row_mask:0xf bank_mask:0xf
	v_add_f32_dpp v13, v12, v12 row_half_mirror row_mask:0xf bank_mask:0xf
	v_add_f32_dpp v17, v16, v16 row_half_mirror row_mask:0xf bank_mask:0xf
	v_add_f32_dpp v21, v20, v20 row_half_mirror row_mask:0xf bank_mask:0xf
	v_add_f32_dpp v25, v24, v24 row_half_mirror row_mask:0xf bank_mask:0xf
	v_add_f32_dpp v29, v28, v28 row_half_mirror row_mask:0xf bank_mask:0xf
	v_add_f32_dpp v33, v32, v32 row_half_mirror row_mask:0xf bank_mask:0xf
	v_add_f32_dpp v37, v36, v36 row_half_mirror row_mask:0xf bank_mask:0xf
	v_add_f32_dpp v41, v40, v40 row_half_mirror row_mask:0xf bank_mask:0xf
	v_add_f32_dpp v45, v44, v44 row_half_mirror row_mask:0xf bank_mask:0xf
	v_add_f32_dpp v49, v48, v48 row_half_mirror row_mask:0xf bank_mask:0xf
	v_add_f32_dpp v53, v52, v52 row_half_mirror row_mask:0xf bank_mask:0xf
	v_add_f32_dpp v57, v56, v56 row_half_mirror row_mask:0xf bank_mask:0xf
	v_add_f32_dpp v61, v60, v60 row_half_mirror row_mask:0xf bank_mask:0xf
	v_add_f32_dpp v65, v64, v64 row_half_mirror row_mask:0xf bank_mask:0xf
	v_add_f32_dpp v69, v68, v68 row_half_mirror row_mask:0xf bank_mask:0xf
	v_add_f32_dpp v73, v72, v72 row_half_mirror row_mask:0xf bank_mask:0xf
	v_add_f32_dpp v77, v76, v76 row_half_mirror row_mask:0xf bank_mask:0xf
	v_add_f32_dpp v81, v80, v80 row_half_mirror row_mask:0xf bank_mask:0xf
	v_add_f32_dpp v85, v84, v84 row_half_mirror row_mask:0xf bank_mask:0xf
	v_add_f32_dpp v89, v88, v88 row_half_mirror row_mask:0xf bank_mask:0xf
	v_add_f32_dpp v93, v92, v92 row_half_mirror row_mask:0xf bank_mask:0xf
	v_add_f32_dpp v8, v9, v9 row_mirror row_mask:0xf bank_mask:0xf
	v_add_f32_dpp v12, v13, v13 row_mirror row_mask:0xf bank_mask:0xf
	v_add_f32_dpp v16, v17, v17 row_mirror row_mask:0xf bank_mask:0xf
	v_add_f32_dpp v20, v21, v21 row_mirror row_mask:0xf bank_mask:0xf
	v_add_f32_dpp v24, v25, v25 row_mirror row_mask:0xf bank_mask:0xf
	v_add_f32_dpp v28, v29, v29 row_mirror row_mask:0xf bank_mask:0xf
	v_add_f32_dpp v32, v33, v33 row_mirror row_mask:0xf bank_mask:0xf
	v_add_f32_dpp v36, v37, v37 row_mirror row_mask:0xf bank_mask:0xf
	v_add_f32_dpp v40, v41, v41 row_mirror row_mask:0xf bank_mask:0xf
	v_add_f32_dpp v44, v45, v45 row_mirror row_mask:0xf bank_mask:0xf
	v_add_f32_dpp v48, v49, v49 row_mirror row_mask:0xf bank_mask:0xf
	v_add_f32_dpp v52, v53, v53 row_mirror row_mask:0xf bank_mask:0xf
	v_add_f32_dpp v56, v57, v57 row_mirror row_mask:0xf bank_mask:0xf
	v_add_f32_dpp v60, v61, v61 row_mirror row_mask:0xf bank_mask:0xf
	v_add_f32_dpp v64, v65, v65 row_mirror row_mask:0xf bank_mask:0xf
	v_add_f32_dpp v68, v69, v69 row_mirror row_mask:0xf bank_mask:0xf
	v_add_f32_dpp v72, v73, v73 row_mirror row_mask:0xf bank_mask:0xf
	v_add_f32_dpp v76, v77, v77 row_mirror row_mask:0xf bank_mask:0xf
	v_add_f32_dpp v80, v81, v81 row_mirror row_mask:0xf bank_mask:0xf
	v_add_f32_dpp v84, v85, v85 row_mirror row_mask:0xf bank_mask:0xf
	v_add_f32_dpp v88, v89, v89 row_mirror row_mask:0xf bank_mask:0xf
	v_add_f32_dpp v92, v93, v93 row_mirror row_mask:0xf bank_mask:0xf
	v_fmamk_f32 v8, v8, 0x3a000000, v223
	v_cmp_gt_f32_e32 vcc, s56, v8
	v_mul_f32_e32 v9, 0x4b800000, v8
	s_nop 0
	v_cndmask_b32_e32 v8, v8, v9, vcc
	v_rsq_f32_e32 v8, v8
	s_nop 0
	v_mul_f32_e32 v9, 0x45800000, v8
	v_cndmask_b32_e32 v8, v8, v9, vcc
	v_fmamk_f32 v12, v12, 0x3a000000, v223
	v_cmp_gt_f32_e32 vcc, s56, v12
	v_mul_f32_e32 v13, 0x4b800000, v12
	s_nop 0
	v_cndmask_b32_e32 v12, v12, v13, vcc
	v_rsq_f32_e32 v12, v12
	s_nop 0
	v_mul_f32_e32 v13, 0x45800000, v12
	v_cndmask_b32_e32 v12, v12, v13, vcc
	v_fmamk_f32 v16, v16, 0x3a000000, v223
	v_cmp_gt_f32_e32 vcc, s56, v16
	v_mul_f32_e32 v17, 0x4b800000, v16
	s_nop 0
	v_cndmask_b32_e32 v16, v16, v17, vcc
	v_rsq_f32_e32 v16, v16
	s_nop 0
	v_mul_f32_e32 v17, 0x45800000, v16
	v_cndmask_b32_e32 v16, v16, v17, vcc
	v_fmamk_f32 v20, v20, 0x3a000000, v223
	v_cmp_gt_f32_e32 vcc, s56, v20
	v_mul_f32_e32 v21, 0x4b800000, v20
	s_nop 0
	v_cndmask_b32_e32 v20, v20, v21, vcc
	v_rsq_f32_e32 v20, v20
	s_nop 0
	v_mul_f32_e32 v21, 0x45800000, v20
	v_cndmask_b32_e32 v20, v20, v21, vcc
	v_fmamk_f32 v24, v24, 0x3a000000, v223
	v_cmp_gt_f32_e32 vcc, s56, v24
	v_mul_f32_e32 v25, 0x4b800000, v24
	s_nop 0
	v_cndmask_b32_e32 v24, v24, v25, vcc
	v_rsq_f32_e32 v24, v24
	s_nop 0
	v_mul_f32_e32 v25, 0x45800000, v24
	v_cndmask_b32_e32 v24, v24, v25, vcc
	v_fmamk_f32 v28, v28, 0x3a000000, v223
	v_cmp_gt_f32_e32 vcc, s56, v28
	v_mul_f32_e32 v29, 0x4b800000, v28
	s_nop 0
	v_cndmask_b32_e32 v28, v28, v29, vcc
	v_rsq_f32_e32 v28, v28
	s_nop 0
	v_mul_f32_e32 v29, 0x45800000, v28
	v_cndmask_b32_e32 v28, v28, v29, vcc
	v_fmamk_f32 v32, v32, 0x3a000000, v223
	v_cmp_gt_f32_e32 vcc, s56, v32
	v_mul_f32_e32 v33, 0x4b800000, v32
	s_nop 0
	v_cndmask_b32_e32 v32, v32, v33, vcc
	v_rsq_f32_e32 v32, v32
	s_nop 0
	v_mul_f32_e32 v33, 0x45800000, v32
	v_cndmask_b32_e32 v32, v32, v33, vcc
	v_fmamk_f32 v36, v36, 0x3a000000, v223
	v_cmp_gt_f32_e32 vcc, s56, v36
	v_mul_f32_e32 v37, 0x4b800000, v36
	s_nop 0
	v_cndmask_b32_e32 v36, v36, v37, vcc
	v_rsq_f32_e32 v36, v36
	s_nop 0
	v_mul_f32_e32 v37, 0x45800000, v36
	v_cndmask_b32_e32 v36, v36, v37, vcc
	v_fmamk_f32 v40, v40, 0x3a000000, v223
	v_cmp_gt_f32_e32 vcc, s56, v40
	v_mul_f32_e32 v41, 0x4b800000, v40
	s_nop 0
	v_cndmask_b32_e32 v40, v40, v41, vcc
	v_rsq_f32_e32 v40, v40
	s_nop 0
	v_mul_f32_e32 v41, 0x45800000, v40
	v_cndmask_b32_e32 v40, v40, v41, vcc
	v_fmamk_f32 v44, v44, 0x3a000000, v223
	v_cmp_gt_f32_e32 vcc, s56, v44
	v_mul_f32_e32 v45, 0x4b800000, v44
	s_nop 0
	v_cndmask_b32_e32 v44, v44, v45, vcc
	v_rsq_f32_e32 v44, v44
	s_nop 0
	v_mul_f32_e32 v45, 0x45800000, v44
	v_cndmask_b32_e32 v44, v44, v45, vcc
	v_fmamk_f32 v48, v48, 0x3a000000, v223
	v_cmp_gt_f32_e32 vcc, s56, v48
	v_mul_f32_e32 v49, 0x4b800000, v48
	s_nop 0
	v_cndmask_b32_e32 v48, v48, v49, vcc
	v_rsq_f32_e32 v48, v48
	s_nop 0
	v_mul_f32_e32 v49, 0x45800000, v48
	v_cndmask_b32_e32 v48, v48, v49, vcc
	v_fmamk_f32 v52, v52, 0x3a000000, v223
	v_cmp_gt_f32_e32 vcc, s56, v52
	v_mul_f32_e32 v53, 0x4b800000, v52
	s_nop 0
	v_cndmask_b32_e32 v52, v52, v53, vcc
	v_rsq_f32_e32 v52, v52
	s_nop 0
	v_mul_f32_e32 v53, 0x45800000, v52
	v_cndmask_b32_e32 v52, v52, v53, vcc
	v_fmamk_f32 v56, v56, 0x3a000000, v223
	v_cmp_gt_f32_e32 vcc, s56, v56
	v_mul_f32_e32 v57, 0x4b800000, v56
	s_nop 0
	v_cndmask_b32_e32 v56, v56, v57, vcc
	v_rsq_f32_e32 v56, v56
	s_nop 0
	v_mul_f32_e32 v57, 0x45800000, v56
	v_cndmask_b32_e32 v56, v56, v57, vcc
	v_fmamk_f32 v60, v60, 0x3a000000, v223
	v_cmp_gt_f32_e32 vcc, s56, v60
	v_mul_f32_e32 v61, 0x4b800000, v60
	s_nop 0
	v_cndmask_b32_e32 v60, v60, v61, vcc
	v_rsq_f32_e32 v60, v60
	s_nop 0
	v_mul_f32_e32 v61, 0x45800000, v60
	v_cndmask_b32_e32 v60, v60, v61, vcc
	v_fmamk_f32 v64, v64, 0x3a000000, v223
	v_cmp_gt_f32_e32 vcc, s56, v64
	v_mul_f32_e32 v65, 0x4b800000, v64
	s_nop 0
	v_cndmask_b32_e32 v64, v64, v65, vcc
	v_rsq_f32_e32 v64, v64
	s_nop 0
	v_mul_f32_e32 v65, 0x45800000, v64
	v_cndmask_b32_e32 v64, v64, v65, vcc
	v_fmamk_f32 v68, v68, 0x3a000000, v223
	v_cmp_gt_f32_e32 vcc, s56, v68
	v_mul_f32_e32 v69, 0x4b800000, v68
	s_nop 0
	v_cndmask_b32_e32 v68, v68, v69, vcc
	v_rsq_f32_e32 v68, v68
	s_nop 0
	v_mul_f32_e32 v69, 0x45800000, v68
	v_cndmask_b32_e32 v68, v68, v69, vcc
	v_fmamk_f32 v72, v72, 0x3a000000, v223
	v_cmp_gt_f32_e32 vcc, s56, v72
	v_mul_f32_e32 v73, 0x4b800000, v72
	s_nop 0
	v_cndmask_b32_e32 v72, v72, v73, vcc
	v_rsq_f32_e32 v72, v72
	s_nop 0
	v_mul_f32_e32 v73, 0x45800000, v72
	v_cndmask_b32_e32 v72, v72, v73, vcc
	v_fmamk_f32 v76, v76, 0x3a000000, v223
	v_cmp_gt_f32_e32 vcc, s56, v76
	v_mul_f32_e32 v77, 0x4b800000, v76
	s_nop 0
	v_cndmask_b32_e32 v76, v76, v77, vcc
	v_rsq_f32_e32 v76, v76
	s_nop 0
	v_mul_f32_e32 v77, 0x45800000, v76
	v_cndmask_b32_e32 v76, v76, v77, vcc
	v_fmamk_f32 v80, v80, 0x3a000000, v223
	v_cmp_gt_f32_e32 vcc, s56, v80
	v_mul_f32_e32 v81, 0x4b800000, v80
	s_nop 0
	v_cndmask_b32_e32 v80, v80, v81, vcc
	v_rsq_f32_e32 v80, v80
	s_nop 0
	v_mul_f32_e32 v81, 0x45800000, v80
	v_cndmask_b32_e32 v80, v80, v81, vcc
	v_fmamk_f32 v84, v84, 0x3a000000, v223
	v_cmp_gt_f32_e32 vcc, s56, v84
	v_mul_f32_e32 v85, 0x4b800000, v84
	s_nop 0
	v_cndmask_b32_e32 v84, v84, v85, vcc
	v_rsq_f32_e32 v84, v84
	s_nop 0
	v_mul_f32_e32 v85, 0x45800000, v84
	v_cndmask_b32_e32 v84, v84, v85, vcc
	v_fmamk_f32 v88, v88, 0x3a000000, v223
	v_cmp_gt_f32_e32 vcc, s56, v88
	v_mul_f32_e32 v89, 0x4b800000, v88
	s_nop 0
	v_cndmask_b32_e32 v88, v88, v89, vcc
	v_rsq_f32_e32 v88, v88
	s_nop 0
	v_mul_f32_e32 v89, 0x45800000, v88
	v_cndmask_b32_e32 v88, v88, v89, vcc
	v_fmamk_f32 v92, v92, 0x3a000000, v223
	v_cmp_gt_f32_e32 vcc, s56, v92
	v_mul_f32_e32 v93, 0x4b800000, v92
	s_nop 0
	v_cndmask_b32_e32 v92, v92, v93, vcc
	v_rsq_f32_e32 v92, v92
	s_nop 0
	v_mul_f32_e32 v93, 0x45800000, v92
	v_cndmask_b32_e32 v92, v92, v93, vcc
	s_mov_b64 exec, s[80:81]
	ds_write_b32 v3, v8
	ds_write_b32 v3, v12 offset:128
	ds_write_b32 v3, v16 offset:256
	ds_write_b32 v3, v20 offset:384
	ds_write_b32 v3, v24 offset:512
	ds_write_b32 v3, v28 offset:640
	ds_write_b32 v3, v32 offset:768
	ds_write_b32 v3, v36 offset:896
	ds_write_b32 v3, v40 offset:1024
	ds_write_b32 v3, v44 offset:1152
	ds_write_b32 v3, v48 offset:1280
	ds_write_b32 v3, v52 offset:1408
	ds_write_b32 v3, v56 offset:1536
	ds_write_b32 v3, v60 offset:1664
	ds_write_b32 v3, v64 offset:1792
	ds_write_b32 v3, v68 offset:1920
	ds_write_b32 v3, v72 offset:2048
	ds_write_b32 v3, v76 offset:2176
	ds_write_b32 v3, v80 offset:2304
	ds_write_b32 v3, v84 offset:2432
	ds_write_b32 v3, v88 offset:2560
	ds_write_b32 v3, v92 offset:2688
	s_mov_b64 exec, -1
	v_add_u32_e32 v3, 0xb00, v3
	s_sub_i32 s30, s30, 1
	s_cmp_lg_u32 s30, 0
	s_cbranch_scc1 .Lrq_batch
.LBB0_112:
	s_and_b64 s[42:43], s[8:9], s[74:75]
	s_andn2_b64 vcc, exec, s[42:43]
	s_waitcnt lgkmcnt(0)
	s_barrier
	s_cbranch_vccnz .LBB0_131
	s_and_b64 s[42:43], s[76:77], exec
	s_cselect_b32 s39, 0, 41
	s_lshl_b32 s30, s34, 2
	s_and_b32 s30, s30, 0x7c
	s_add_i32 s74, s30, s36
	v_lshl_or_b32 v0, s74, 6, v116
	v_ashrrev_i32_e32 v1, 31, v0
	s_mul_i32 s30, s70, 0x810
	s_mov_b64 s[80:81], -1
	s_and_b64 vcc, exec, s[72:73]
	v_lshl_add_u64 v[96:97], v[0:1], 3, s[24:25]
	v_lshl_or_b32 v98, s74, 8, v116
	v_add_u32_e32 v138, s30, v123
	v_add_u32_e32 v139, s30, v154
	s_cbranch_vccz .LBB0_119
	s_lshl_b32 s78, s74, 4
	s_ashr_i32 s79, s78, 31
	v_lshl_or_b32 v100, s74, 8, v116
	v_lshl_add_u64 v[0:1], s[78:79], 2, v[118:119]
	v_ashrrev_i32_e32 v101, 31, v100
	v_add_u32_e32 v102, s30, v123
	global_load_dwordx2 v[12:13], v[96:97], off
	global_load_dwordx4 v[64:67], v[0:1], off offset:16
	global_load_dwordx4 v[68:71], v[0:1], off
	v_lshl_add_u64 v[0:1], v[100:101], 4, s[62:63]
	v_ashrrev_i32_e32 v103, 31, v102
	global_load_dwordx4 v[72:75], v[0:1], off
	global_load_dwordx4 v[76:79], v[0:1], off offset:1024
	global_load_dwordx4 v[80:83], v[0:1], off offset:2048
	global_load_dwordx4 v[84:87], v[0:1], off offset:3072
	v_lshlrev_b64 v[0:1], 12, v[102:103]
	s_lshl_b64 s[42:43], s[78:79], 1
	v_lshl_add_u64 v[0:1], s[22:23], 0, v[0:1]
	v_lshl_add_u64 v[0:1], v[0:1], 0, s[42:43]
	v_mov_b32_e32 v137, v193
	v_lshl_add_u64 v[0:1], v[0:1], 0, v[136:137]
	global_load_dwordx4 v[8:11], v[0:1], off
	v_add_u32_e32 v137, s30, v154
	v_mov_b32_e32 v140, 0
	v_lshl_add_u64 v[106:107], v[120:121], 0, s[42:43]
	v_mov_b64_e32 v[104:105], v[100:101]
	s_mov_b32 s42, 0
	v_mov_b32_e32 v99, v125
	v_mov_b32_e32 v114, v137
	v_mov_b32_e32 v141, v140
	s_waitcnt vmcnt(7)
	v_xor_b32_e32 v108, 0x80000000, v13
	v_mov_b32_e32 v110, v12
	v_mov_b32_e32 v111, v12
	v_mov_b32_e32 v109, v13
	v_mov_b32_e32 v112, v13
	v_mov_b32_e32 v113, v108
	s_waitcnt vmcnt(0)
	v_lshlrev_b32_e32 v6, 16, v11
	v_and_b32_e32 v7, 0xffff0000, v11
	v_lshlrev_b32_e32 v2, 16, v9
	v_and_b32_e32 v3, 0xffff0000, v9
	v_lshlrev_b32_e32 v4, 16, v10
	v_and_b32_e32 v5, 0xffff0000, v10
	v_lshlrev_b32_e32 v0, 16, v8
	v_and_b32_e32 v1, 0xffff0000, v8
	v_mov_b64_e32 v[94:95], v[6:7]
	v_mov_b64_e32 v[90:91], v[2:3]
	v_mov_b64_e32 v[92:93], v[4:5]
	v_mov_b64_e32 v[88:89], v[0:1]
	s_branch .LBB0_116

.LBB0_121:
	v_or_b32_e32 v8, 64, v100
	v_lshlrev_b64 v[4:5], 4, v[104:105]
	v_ashrrev_i32_e32 v9, 31, v8
	v_lshl_add_u64 v[6:7], s[64:65], 0, v[4:5]
	v_lshlrev_b64 v[10:11], 4, v[8:9]
	global_load_dwordx2 v[138:139], v[96:97], off
	v_lshl_add_u64 v[8:9], s[64:65], 0, v[10:11]
	global_load_dwordx4 v[64:67], v[6:7], off
	global_load_dwordx4 v[68:71], v[8:9], off
	v_or_b32_e32 v6, 0x80, v100
	v_ashrrev_i32_e32 v7, 31, v6
	v_or_b32_e32 v8, 0xc0, v100
	v_lshlrev_b64 v[16:17], 2, v[0:1]
	s_and_b64 s[42:43], s[76:77], exec
	v_lshlrev_b64 v[12:13], 4, v[6:7]
	v_ashrrev_i32_e32 v9, 31, v8
	v_lshl_add_u64 v[18:19], s[26:27], 0, v[16:17]
	v_lshl_add_u64 v[6:7], s[64:65], 0, v[12:13]
	v_lshlrev_b64 v[14:15], 4, v[8:9]
	v_lshlrev_b32_e32 v3, 2, v122
	v_readfirstlane_b32 s42, v18
	v_readfirstlane_b32 s43, v19
	s_cselect_b32 s30, 41, 0x41
	v_lshl_add_u64 v[8:9], s[64:65], 0, v[14:15]
	global_load_dwordx4 v[72:75], v[6:7], off
	global_load_dwordx4 v[76:79], v[8:9], off
	s_nop 0
	global_load_dwordx4 v[80:83], v3, s[42:43] offset:16
	global_load_dwordx4 v[84:87], v3, s[42:43]
	s_lshl_b32 s42, s39, 5
	v_add_u32_e32 v6, s42, v102
	v_ashrrev_i32_e32 v7, 31, v6
	v_lshlrev_b64 v[6:7], 12, v[6:7]
	v_lshlrev_b64 v[0:1], 1, v[0:1]
	v_lshl_add_u64 v[6:7], s[22:23], 0, v[6:7]
	v_lshlrev_b32_e32 v192, 1, v122
	v_lshl_add_u64 v[6:7], v[6:7], 0, v[0:1]
	v_lshl_add_u64 v[6:7], v[6:7], 0, v[192:193]
	global_load_dwordx4 v[6:9], v[6:7], off
	v_lshl_add_u64 v[16:17], v[126:127], 0, v[16:17]
	v_lshl_add_u64 v[4:5], s[62:63], 0, v[4:5]
	global_load_dwordx4 v[88:91], v[16:17], off
	v_lshl_add_u64 v[10:11], s[62:63], 0, v[10:11]
	global_load_dwordx4 v[92:95], v[4:5], off
	global_load_dwordx4 v[96:99], v[10:11], off
	v_lshl_add_u64 v[4:5], s[62:63], 0, v[12:13]
	v_lshl_add_u64 v[10:11], s[62:63], 0, v[14:15]
	global_load_dwordx4 v[100:103], v[4:5], off
	global_load_dwordx4 v[104:107], v[10:11], off
	v_add_u32_e32 v164, v155, v2
	v_lshl_add_u64 v[2:3], s[22:23], 0, v[0:1]
	v_lshl_add_u64 v[144:145], v[2:3], 0, v[192:193]
	v_lshlrev_b32_e32 v192, 1, v124
	v_lshl_add_u64 v[146:147], v[2:3], 0, v[192:193]
	v_lshl_add_u64 v[142:143], v[128:129], 0, v[0:1]
	s_lshl_b32 s43, s39, 7
	v_lshlrev_b32_e32 v192, 2, v124
	v_add_u32_e32 v165, s43, v161
	v_add_u32_e32 v166, s43, v125
	s_sub_i32 s43, 32, s42
	v_lshl_add_u64 v[148:149], v[18:19], 0, v[192:193]
	global_load_dwordx4 v[182:185], v[148:149], off
	s_waitcnt vmcnt(13)
	v_xor_b32_e32 v151, 0x80000000, v139
	v_mov_b32_e32 v152, v138
	v_mov_b32_e32 v153, v138
	v_mov_b32_e32 v150, v139
	v_mov_b32_e32 v138, v151
	s_waitcnt vmcnt(6)
	v_lshlrev_b32_e32 v2, 16, v9
	v_and_b32_e32 v3, 0xffff0000, v9
	v_lshlrev_b32_e32 v4, 16, v6
	v_and_b32_e32 v5, 0xffff0000, v6
	v_lshlrev_b32_e32 v6, 16, v7
	v_and_b32_e32 v7, 0xffff0000, v7
	v_lshlrev_b32_e32 v0, 16, v8
	v_and_b32_e32 v1, 0xffff0000, v8
	v_mov_b64_e32 v[114:115], v[2:3]
	v_mov_b64_e32 v[110:111], v[6:7]
	v_mov_b64_e32 v[112:113], v[0:1]
	v_mov_b64_e32 v[108:109], v[4:5]
	s_waitcnt vmcnt(0)
	s_branch .LBB0_123

.LBB0_522:
	s_add_i32 vcc_lo, s74, 2
	s_add_u32 s76, s72, 0x80
	s_addc_u32 s75, s73, 0
	s_add_i32 vcc_hi, 0, 0x10000
	v_add_u32_e32 v140, vcc_hi, v237
	s_waitcnt lgkmcnt(0)
	ds_read_b128 v[128:131], v140
	ds_read_b128 v[132:135], v140 offset:1024
	ds_read_b128 v[136:139], v140 offset:2048
	ds_read_b128 v[140:143], v140 offset:3072
	s_cmp_eq_u32 s50, s74
	s_cselect_b32 s74, s68, s76
	s_cselect_b32 s75, s69, s75
	s_cselect_b32 s77, s71, s79
	s_cselect_b32 s76, s70, s78
	v_lshl_add_u64 v[176:177], s[72:73], 0, v[206:207]
	s_add_i32 m0, s93, 0xc000
	ds_read_b128 v[144:147], v240
	ds_read_b128 v[148:151], v240 offset:1024
	ds_read_b128 v[152:155], v240 offset:2048
	ds_read_b128 v[156:159], v240 offset:3072
	ds_read_b128 v[160:163], v240 offset:4096
	ds_read_b128 v[164:167], v240 offset:5120
	ds_read_b128 v[168:171], v240 offset:6144
	ds_read_b128 v[172:175], v240 offset:7168
	global_load_lds_dwordx4 v[176:177], off
	v_lshl_add_u64 v[176:177], s[72:73], 0, v[208:209]
	s_add_i32 m0, s93, 0xe000
	s_nop 0
	global_load_lds_dwordx4 v[176:177], off
	s_waitcnt lgkmcnt(8)
	s_barrier
	s_waitcnt lgkmcnt(0)
	v_mfma_f32_16x16x32_bf16 v[124:127], v[128:131], v[144:147], v[124:127]
	v_mfma_f32_16x16x32_bf16 v[120:123], v[136:139], v[144:147], v[120:123]
	v_mfma_f32_16x16x32_bf16 v[116:119], v[128:131], v[152:155], v[116:119]
	v_mfma_f32_16x16x32_bf16 v[112:115], v[136:139], v[152:155], v[112:115]
	v_mfma_f32_16x16x32_bf16 v[100:103], v[128:131], v[160:163], v[100:103]
	v_mfma_f32_16x16x32_bf16 v[96:99], v[136:139], v[160:163], v[96:99]
	v_mfma_f32_16x16x32_bf16 v[84:87], v[128:131], v[168:171], v[84:87]
	v_mfma_f32_16x16x32_bf16 v[80:83], v[136:139], v[168:171], v[80:83]
	v_mfma_f32_16x16x32_bf16 v[124:127], v[132:135], v[148:151], v[124:127]
	v_mfma_f32_16x16x32_bf16 v[120:123], v[140:143], v[148:151], v[120:123]
	v_mfma_f32_16x16x32_bf16 v[116:119], v[132:135], v[156:159], v[116:119]
	v_mfma_f32_16x16x32_bf16 v[112:115], v[140:143], v[156:159], v[112:115]
	v_mfma_f32_16x16x32_bf16 v[100:103], v[132:135], v[164:167], v[100:103]
	v_mfma_f32_16x16x32_bf16 v[96:99], v[140:143], v[164:167], v[96:99]
	v_mfma_f32_16x16x32_bf16 v[84:87], v[132:135], v[172:175], v[84:87]
	v_mfma_f32_16x16x32_bf16 v[80:83], v[140:143], v[172:175], v[80:83]
	s_barrier
	s_add_i32 s31, 0, 0x14000
	s_add_i32 vcc_hi, vcc_hi, s87
	v_add_u32_e32 v188, s31, v237
	v_lshl_add_u64 v[210:211], s[76:77], 0, v[196:197]
	s_mov_b32 m0, vcc_hi
	ds_read_b128 v[176:179], v188
	ds_read_b128 v[180:183], v188 offset:1024
	ds_read_b128 v[184:187], v188 offset:2048
	ds_read_b128 v[188:191], v188 offset:3072
	global_load_lds_dwordx4 v[210:211], off
	v_lshl_add_u64 v[212:213], s[76:77], 0, v[200:201]
	s_add_i32 m0, vcc_hi, 0x2000
	s_nop 0
	global_load_lds_dwordx4 v[212:213], off
	s_barrier
	s_waitcnt lgkmcnt(0)
	v_mfma_f32_16x16x32_bf16 v[108:111], v[176:179], v[144:147], v[108:111]
	v_mfma_f32_16x16x32_bf16 v[104:107], v[184:187], v[144:147], v[104:107]
	v_mfma_f32_16x16x32_bf16 v[92:95], v[176:179], v[152:155], v[92:95]
	v_mfma_f32_16x16x32_bf16 v[88:91], v[184:187], v[152:155], v[88:91]
	v_mfma_f32_16x16x32_bf16 v[76:79], v[176:179], v[160:163], v[76:79]
	v_mfma_f32_16x16x32_bf16 v[72:75], v[184:187], v[160:163], v[72:75]
	v_mfma_f32_16x16x32_bf16 v[68:71], v[176:179], v[168:171], v[68:71]
	v_mfma_f32_16x16x32_bf16 v[64:67], v[184:187], v[168:171], v[64:67]
	v_mfma_f32_16x16x32_bf16 v[108:111], v[180:183], v[148:151], v[108:111]
	v_mfma_f32_16x16x32_bf16 v[104:107], v[188:191], v[148:151], v[104:107]
	v_mfma_f32_16x16x32_bf16 v[92:95], v[180:183], v[156:159], v[92:95]
	v_mfma_f32_16x16x32_bf16 v[88:91], v[188:191], v[156:159], v[88:91]
	v_mfma_f32_16x16x32_bf16 v[76:79], v[180:183], v[164:167], v[76:79]
	v_mfma_f32_16x16x32_bf16 v[72:75], v[188:191], v[164:167], v[72:75]
	v_mfma_f32_16x16x32_bf16 v[68:71], v[180:183], v[172:175], v[68:71]
	v_mfma_f32_16x16x32_bf16 v[64:67], v[188:191], v[172:175], v[64:67]
	s_mov_b32 m0, s93
	v_lshl_add_u64 v[214:215], s[74:75], 0, v[194:195]
	s_barrier
	ds_read_b128 v[144:147], v240 offset:16384
	ds_read_b128 v[148:151], v240 offset:17408
	ds_read_b128 v[152:155], v240 offset:18432
	ds_read_b128 v[156:159], v240 offset:19456
	ds_read_b128 v[160:163], v240 offset:20480
	ds_read_b128 v[164:167], v240 offset:21504
	ds_read_b128 v[168:171], v240 offset:22528
	ds_read_b128 v[172:175], v240 offset:23552
	global_load_lds_dwordx4 v[214:215], off
	v_lshl_add_u64 v[216:217], s[74:75], 0, v[198:199]
	s_mov_b32 m0, s54
	s_nop 0
	global_load_lds_dwordx4 v[216:217], off
	s_barrier
	s_waitcnt lgkmcnt(0)
	v_mfma_f32_16x16x32_bf16 v[60:63], v[128:131], v[144:147], v[60:63]
	v_mfma_f32_16x16x32_bf16 v[56:59], v[136:139], v[144:147], v[56:59]
	v_mfma_f32_16x16x32_bf16 v[52:55], v[128:131], v[152:155], v[52:55]
	v_mfma_f32_16x16x32_bf16 v[48:51], v[136:139], v[152:155], v[48:51]
	v_mfma_f32_16x16x32_bf16 v[36:39], v[128:131], v[160:163], v[36:39]
	v_mfma_f32_16x16x32_bf16 v[32:35], v[136:139], v[160:163], v[32:35]
	v_mfma_f32_16x16x32_bf16 v[20:23], v[128:131], v[168:171], v[20:23]
	v_mfma_f32_16x16x32_bf16 v[16:19], v[136:139], v[168:171], v[16:19]
	v_mfma_f32_16x16x32_bf16 v[60:63], v[132:135], v[148:151], v[60:63]
	v_mfma_f32_16x16x32_bf16 v[56:59], v[140:143], v[148:151], v[56:59]
	v_mfma_f32_16x16x32_bf16 v[52:55], v[132:135], v[156:159], v[52:55]
	v_mfma_f32_16x16x32_bf16 v[48:51], v[140:143], v[156:159], v[48:51]
	v_mfma_f32_16x16x32_bf16 v[36:39], v[132:135], v[164:167], v[36:39]
	v_mfma_f32_16x16x32_bf16 v[32:35], v[140:143], v[164:167], v[32:35]
	v_mfma_f32_16x16x32_bf16 v[20:23], v[132:135], v[172:175], v[20:23]
	v_mfma_f32_16x16x32_bf16 v[16:19], v[140:143], v[172:175], v[16:19]
	s_barrier
	s_add_u32 s76, s76, s20
	s_addc_u32 s77, s77, 0
	s_add_i32 s31, s31, s87
	v_lshl_add_u64 v[218:219], s[76:77], 0, v[196:197]
	s_mov_b32 m0, s31
	v_lshl_add_u64 v[220:221], s[76:77], 0, v[200:201]
	global_load_lds_dwordx4 v[218:219], off
	s_add_i32 m0, s31, 0x2000
	s_nop 0
	global_load_lds_dwordx4 v[220:221], off
	s_waitcnt vmcnt(6)
	s_barrier
	v_mfma_f32_16x16x32_bf16 v[44:47], v[176:179], v[144:147], v[44:47]
	v_mfma_f32_16x16x32_bf16 v[40:43], v[184:187], v[144:147], v[40:43]
	v_mfma_f32_16x16x32_bf16 v[28:31], v[176:179], v[152:155], v[28:31]
	v_mfma_f32_16x16x32_bf16 v[24:27], v[184:187], v[152:155], v[24:27]
	v_mfma_f32_16x16x32_bf16 v[12:15], v[176:179], v[160:163], v[12:15]
	v_mfma_f32_16x16x32_bf16 v[8:11], v[184:187], v[160:163], v[8:11]
	v_mfma_f32_16x16x32_bf16 v[4:7], v[176:179], v[168:171], v[4:7]
	v_mfma_f32_16x16x32_bf16 v[0:3], v[184:187], v[168:171], v[0:3]
	v_mfma_f32_16x16x32_bf16 v[44:47], v[180:183], v[148:151], v[44:47]
	v_mfma_f32_16x16x32_bf16 v[40:43], v[188:191], v[148:151], v[40:43]
	v_mfma_f32_16x16x32_bf16 v[28:31], v[180:183], v[156:159], v[28:31]
	v_mfma_f32_16x16x32_bf16 v[24:27], v[188:191], v[156:159], v[24:27]
	v_mfma_f32_16x16x32_bf16 v[12:15], v[180:183], v[164:167], v[12:15]
	v_mfma_f32_16x16x32_bf16 v[8:11], v[188:191], v[164:167], v[8:11]
	v_mfma_f32_16x16x32_bf16 v[4:7], v[180:183], v[172:175], v[4:7]
	v_mfma_f32_16x16x32_bf16 v[0:3], v[188:191], v[172:175], v[0:3]
	s_add_i32 s31, 0, 0x18000
	v_add_u32_e32 v140, s31, v237
	s_barrier
	ds_read_b128 v[128:131], v140
	ds_read_b128 v[132:135], v140 offset:1024
	ds_read_b128 v[136:139], v140 offset:2048
	ds_read_b128 v[140:143], v140 offset:3072
	s_add_u32 s74, s74, s20
	s_addc_u32 s75, s75, 0
	s_mov_b32 m0, s34
	v_lshl_add_u64 v[176:177], s[74:75], 0, v[194:195]
	ds_read_b128 v[144:147], v240 offset:32768
	ds_read_b128 v[148:151], v240 offset:33792
	ds_read_b128 v[152:155], v240 offset:34816
	ds_read_b128 v[156:159], v240 offset:35840
	ds_read_b128 v[160:163], v240 offset:36864
	ds_read_b128 v[164:167], v240 offset:37888
	ds_read_b128 v[168:171], v240 offset:38912
	ds_read_b128 v[172:175], v240 offset:39936
	global_load_lds_dwordx4 v[176:177], off
	v_lshl_add_u64 v[176:177], s[74:75], 0, v[198:199]
	s_mov_b32 m0, s35
	s_nop 0
	global_load_lds_dwordx4 v[176:177], off
	s_waitcnt lgkmcnt(8)
	s_barrier
	s_waitcnt lgkmcnt(0)
	v_mfma_f32_16x16x32_bf16 v[124:127], v[128:131], v[144:147], v[124:127]
	v_mfma_f32_16x16x32_bf16 v[120:123], v[136:139], v[144:147], v[120:123]
	v_mfma_f32_16x16x32_bf16 v[116:119], v[128:131], v[152:155], v[116:119]
	v_mfma_f32_16x16x32_bf16 v[112:115], v[136:139], v[152:155], v[112:115]
	v_mfma_f32_16x16x32_bf16 v[100:103], v[128:131], v[160:163], v[100:103]
	v_mfma_f32_16x16x32_bf16 v[96:99], v[136:139], v[160:163], v[96:99]
	v_mfma_f32_16x16x32_bf16 v[84:87], v[128:131], v[168:171], v[84:87]
	v_mfma_f32_16x16x32_bf16 v[80:83], v[136:139], v[168:171], v[80:83]
	v_mfma_f32_16x16x32_bf16 v[124:127], v[132:135], v[148:151], v[124:127]
	v_mfma_f32_16x16x32_bf16 v[120:123], v[140:143], v[148:151], v[120:123]
	v_mfma_f32_16x16x32_bf16 v[116:119], v[132:135], v[156:159], v[116:119]
	v_mfma_f32_16x16x32_bf16 v[112:115], v[140:143], v[156:159], v[112:115]
	v_mfma_f32_16x16x32_bf16 v[100:103], v[132:135], v[164:167], v[100:103]
	v_mfma_f32_16x16x32_bf16 v[96:99], v[140:143], v[164:167], v[96:99]
	v_mfma_f32_16x16x32_bf16 v[84:87], v[132:135], v[172:175], v[84:87]
	v_mfma_f32_16x16x32_bf16 v[80:83], v[140:143], v[172:175], v[80:83]
	s_barrier
	s_add_i32 s74, 0, 0x1c000
	s_add_i32 s31, s31, s87
	v_add_u32_e32 v188, s74, v237
	v_lshl_add_u64 v[210:211], v[210:211], 0, s[60:61]
	s_mov_b32 m0, s31
	ds_read_b128 v[176:179], v188
	ds_read_b128 v[180:183], v188 offset:1024
	ds_read_b128 v[184:187], v188 offset:2048
	ds_read_b128 v[188:191], v188 offset:3072
	global_load_lds_dwordx4 v[210:211], off
	v_lshl_add_u64 v[210:211], v[212:213], 0, s[60:61]
	s_add_i32 m0, s31, 0x2000
	s_nop 0
	global_load_lds_dwordx4 v[210:211], off
	s_barrier
	s_waitcnt lgkmcnt(0)
	v_mfma_f32_16x16x32_bf16 v[108:111], v[176:179], v[144:147], v[108:111]
	v_mfma_f32_16x16x32_bf16 v[104:107], v[184:187], v[144:147], v[104:107]
	v_mfma_f32_16x16x32_bf16 v[92:95], v[176:179], v[152:155], v[92:95]
	v_mfma_f32_16x16x32_bf16 v[88:91], v[184:187], v[152:155], v[88:91]
	v_mfma_f32_16x16x32_bf16 v[76:79], v[176:179], v[160:163], v[76:79]
	v_mfma_f32_16x16x32_bf16 v[72:75], v[184:187], v[160:163], v[72:75]
	v_mfma_f32_16x16x32_bf16 v[68:71], v[176:179], v[168:171], v[68:71]
	v_mfma_f32_16x16x32_bf16 v[64:67], v[184:187], v[168:171], v[64:67]
	v_mfma_f32_16x16x32_bf16 v[108:111], v[180:183], v[148:151], v[108:111]
	v_mfma_f32_16x16x32_bf16 v[104:107], v[188:191], v[148:151], v[104:107]
	v_mfma_f32_16x16x32_bf16 v[92:95], v[180:183], v[156:159], v[92:95]
	v_mfma_f32_16x16x32_bf16 v[88:91], v[188:191], v[156:159], v[88:91]
	v_mfma_f32_16x16x32_bf16 v[76:79], v[180:183], v[164:167], v[76:79]
	v_mfma_f32_16x16x32_bf16 v[72:75], v[188:191], v[164:167], v[72:75]
	v_mfma_f32_16x16x32_bf16 v[68:71], v[180:183], v[172:175], v[68:71]
	v_mfma_f32_16x16x32_bf16 v[64:67], v[188:191], v[172:175], v[64:67]
	s_mov_b32 m0, s97
	v_lshl_add_u64 v[210:211], v[214:215], 0, s[60:61]
	s_barrier
	ds_read_b128 v[144:147], v240 offset:49152
	ds_read_b128 v[148:151], v240 offset:50176
	ds_read_b128 v[152:155], v240 offset:51200
	ds_read_b128 v[156:159], v240 offset:52224
	ds_read_b128 v[160:163], v240 offset:53248
	ds_read_b128 v[164:167], v240 offset:54272
	ds_read_b128 v[168:171], v240 offset:55296
	ds_read_b128 v[172:175], v240 offset:56320
	global_load_lds_dwordx4 v[210:211], off
	v_lshl_add_u64 v[210:211], v[216:217], 0, s[60:61]
	s_mov_b32 m0, s36
	s_nop 0
	global_load_lds_dwordx4 v[210:211], off
	s_barrier
	s_waitcnt lgkmcnt(0)
	v_mfma_f32_16x16x32_bf16 v[60:63], v[128:131], v[144:147], v[60:63]
	v_mfma_f32_16x16x32_bf16 v[56:59], v[136:139], v[144:147], v[56:59]
	v_mfma_f32_16x16x32_bf16 v[52:55], v[128:131], v[152:155], v[52:55]
	v_mfma_f32_16x16x32_bf16 v[48:51], v[136:139], v[152:155], v[48:51]
	v_mfma_f32_16x16x32_bf16 v[36:39], v[128:131], v[160:163], v[36:39]
	v_mfma_f32_16x16x32_bf16 v[32:35], v[136:139], v[160:163], v[32:35]
	v_mfma_f32_16x16x32_bf16 v[20:23], v[128:131], v[168:171], v[20:23]
	v_mfma_f32_16x16x32_bf16 v[16:19], v[136:139], v[168:171], v[16:19]
	v_mfma_f32_16x16x32_bf16 v[60:63], v[132:135], v[148:151], v[60:63]
	v_mfma_f32_16x16x32_bf16 v[56:59], v[140:143], v[148:151], v[56:59]
	v_mfma_f32_16x16x32_bf16 v[52:55], v[132:135], v[156:159], v[52:55]
	v_mfma_f32_16x16x32_bf16 v[48:51], v[140:143], v[156:159], v[48:51]
	v_mfma_f32_16x16x32_bf16 v[36:39], v[132:135], v[164:167], v[36:39]
	v_mfma_f32_16x16x32_bf16 v[32:35], v[140:143], v[164:167], v[32:35]
	v_mfma_f32_16x16x32_bf16 v[20:23], v[132:135], v[172:175], v[20:23]
	v_mfma_f32_16x16x32_bf16 v[16:19], v[140:143], v[172:175], v[16:19]
	s_barrier
	s_add_i32 s31, s74, s87
	v_lshl_add_u64 v[128:129], v[218:219], 0, s[60:61]
	s_mov_b32 m0, s31
	s_nop 0
	global_load_lds_dwordx4 v[128:129], off
	v_lshl_add_u64 v[128:129], v[220:221], 0, s[60:61]
	s_add_i32 m0, s31, 0x2000
	s_nop 0
	global_load_lds_dwordx4 v[128:129], off
	s_waitcnt vmcnt(6)
	s_barrier
	v_mfma_f32_16x16x32_bf16 v[44:47], v[176:179], v[144:147], v[44:47]
	v_mfma_f32_16x16x32_bf16 v[40:43], v[184:187], v[144:147], v[40:43]
	v_mfma_f32_16x16x32_bf16 v[28:31], v[176:179], v[152:155], v[28:31]
	v_mfma_f32_16x16x32_bf16 v[24:27], v[184:187], v[152:155], v[24:27]
	v_mfma_f32_16x16x32_bf16 v[12:15], v[176:179], v[160:163], v[12:15]
	v_mfma_f32_16x16x32_bf16 v[8:11], v[184:187], v[160:163], v[8:11]
	v_mfma_f32_16x16x32_bf16 v[4:7], v[176:179], v[168:171], v[4:7]
	v_mfma_f32_16x16x32_bf16 v[0:3], v[184:187], v[168:171], v[0:3]
	v_mfma_f32_16x16x32_bf16 v[44:47], v[180:183], v[148:151], v[44:47]
	v_mfma_f32_16x16x32_bf16 v[40:43], v[188:191], v[148:151], v[40:43]
	v_mfma_f32_16x16x32_bf16 v[28:31], v[180:183], v[156:159], v[28:31]
	v_mfma_f32_16x16x32_bf16 v[24:27], v[188:191], v[156:159], v[24:27]
	v_mfma_f32_16x16x32_bf16 v[12:15], v[180:183], v[164:167], v[12:15]
	v_mfma_f32_16x16x32_bf16 v[8:11], v[188:191], v[164:167], v[8:11]
	v_mfma_f32_16x16x32_bf16 v[4:7], v[180:183], v[172:175], v[4:7]
	v_mfma_f32_16x16x32_bf16 v[0:3], v[188:191], v[172:175], v[0:3]
	s_add_u32 s72, s72, 0x100
	s_addc_u32 s73, s73, 0
	s_add_u32 s78, s78, 0x100
	s_addc_u32 s79, s79, 0
	s_cmp_ge_u32 vcc_lo, s30
	s_mov_b32 s74, vcc_lo
	s_barrier
	s_cbranch_scc0 .LBB0_522
	s_cmp_lt_i32 s91, 0
	s_mov_b64 s[72:73], -1
	s_cbranch_scc0 .LBB0_716
	s_lshl_b32 s78, s46, 8
	s_cmp_lt_i32 s81, 2
	s_cbranch_scc1 .LBB0_582
	s_cmp_lt_i32 s81, 3
	s_cbranch_scc1 .LBB0_579
	s_cmp_lg_u32 s81, 3
	s_cbranch_scc0 .LBB0_544
	v_lshl_or_b32 v128, s19, 7, v238
	v_ashrrev_i32_e32 v129, 31, v128
	v_lshl_add_u64 v[144:145], v[128:129], 1, s[24:25]
	v_and_b32_e32 v129, 64, v231
	v_xor_b32_e32 v128, 16, v231
	v_add_u32_e32 v129, 64, v129
	v_cmp_lt_i32_e32 vcc, v128, v129
	v_add_u32_e32 v146, s78, v202
	v_ashrrev_i32_e32 v147, 31, v146
	v_cndmask_b32_e32 v128, v231, v128, vcc
	v_lshlrev_b32_e32 v167, 2, v128
	v_xor_b32_e32 v128, 32, v231
	v_cmp_lt_i32_e32 vcc, v128, v129
	v_or_b32_e32 v156, 16, v146
	v_ashrrev_i32_e32 v157, 31, v156
	v_cndmask_b32_e32 v128, v231, v128, vcc
	v_lshlrev_b32_e32 v166, 2, v128
	v_lshlrev_b64 v[128:129], 12, v[146:147]
	v_lshl_add_u64 v[160:161], v[144:145], 0, v[128:129]
	global_load_dwordx4 v[140:143], v[160:161], off
	v_or_b32_e32 v152, 32, v146
	v_lshlrev_b64 v[128:129], 12, v[156:157]
	v_ashrrev_i32_e32 v153, 31, v152
	v_or_b32_e32 v148, 48, v146
	v_lshl_add_u64 v[158:159], v[144:145], 0, v[128:129]
	v_lshlrev_b64 v[128:129], 12, v[152:153]
	v_ashrrev_i32_e32 v149, 31, v148
	v_lshl_add_u64 v[154:155], v[144:145], 0, v[128:129]
	v_lshlrev_b64 v[128:129], 12, v[148:149]
	v_lshl_add_u64 v[150:151], v[144:145], 0, v[128:129]
	global_load_dwordx4 v[136:139], v[158:159], off
	global_load_dwordx4 v[132:135], v[154:155], off
	global_load_dwordx4 v[128:131], v[150:151], off
	v_mul_f32_e32 v163, 0xbfb8aa3b, v104
	v_exp_f32_e32 v163, v163
	v_mul_f32_e32 v162, 0xbfb8aa3b, v108
	v_exp_f32_e32 v162, v162
	v_add_f32_e32 v163, 1.0, v163
	v_rcp_f32_e32 v164, v163
	v_mul_f32_e32 v163, 0xbfb8aa3b, v109
	v_exp_f32_e32 v163, v163
	v_add_f32_e32 v162, 1.0, v162
	v_rcp_f32_e32 v162, v162
	v_add_f32_e32 v163, 1.0, v163
	v_rcp_f32_e32 v163, v163
	s_waitcnt vmcnt(0)
	v_lshlrev_b32_e32 v168, 16, v140
	v_and_b32_e32 v169, 0xffff0000, v140
	v_mul_f32_e32 v140, 0xbfb8aa3b, v105
	v_exp_f32_e32 v140, v140
	v_pk_fma_f32 v[162:163], v[162:163], v[124:125], v[168:169]
	v_lshlrev_b32_e32 v168, 16, v142
	v_and_b32_e32 v169, 0xffff0000, v142
	v_add_f32_e32 v140, 1.0, v140
	v_rcp_f32_e32 v165, v140
	v_mul_f32_e32 v140, 0xbfb8aa3b, v110
	v_exp_f32_e32 v140, v140
	v_mul_f32_e32 v142, 0xbfb8aa3b, v111
	v_pk_fma_f32 v[164:165], v[164:165], v[120:121], v[168:169]
	v_lshlrev_b32_e32 v170, 16, v141
	v_add_f32_e32 v140, 1.0, v140
	v_rcp_f32_e32 v168, v140
	v_mul_f32_e32 v140, 0xbfb8aa3b, v106
	v_and_b32_e32 v171, 0xffff0000, v141
	v_mul_f32_e32 v141, 0xbfb8aa3b, v107
	v_exp_f32_e32 v140, v140
	v_exp_f32_e32 v142, v142
	v_exp_f32_e32 v141, v141
	v_add_f32_e32 v140, 1.0, v140
	v_add_f32_e32 v142, 1.0, v142
	v_add_f32_e32 v141, 1.0, v141
	v_rcp_f32_e32 v140, v140
	v_rcp_f32_e32 v169, v142
	v_rcp_f32_e32 v141, v141
	v_lshlrev_b32_e32 v142, 16, v143
	v_and_b32_e32 v143, 0xffff0000, v143
	v_pk_fma_f32 v[168:169], v[168:169], v[126:127], v[170:171]
	v_pk_fma_f32 v[170:171], v[140:141], v[122:123], v[142:143]
	v_cvt_pk_bf16_f32 v140, v162, v163
	v_cvt_pk_bf16_f32 v141, v168, v169
	v_cvt_pk_bf16_f32 v142, v164, v165
	v_cvt_pk_bf16_f32 v143, v170, v171
	global_store_dwordx4 v[160:161], v[140:143], off
	v_pk_mul_f32 v[160:161], v[164:165], v[164:165]
	s_nop 0
	v_pk_mul_f32 v[140:141], v[162:163], v[162:163]
	v_pk_mul_f32 v[142:143], v[168:169], v[168:169]
	v_add_f32_e32 v140, v140, v141
	v_add_f32_e32 v142, v142, v143
	v_pk_mul_f32 v[162:163], v[170:171], v[170:171]
	v_add_f32_e32 v140, v140, v142
	v_add_f32_e32 v141, v160, v161
	v_add_f32_e32 v162, v162, v163
	v_add_f32_e32 v140, v141, v140
	v_add_f32_e32 v140, v162, v140
	ds_bpermute_b32 v141, v167, v140
	s_waitcnt lgkmcnt(0)
	v_add_f32_e32 v140, v140, v141
	ds_bpermute_b32 v141, v166, v140
	s_and_saveexec_b64 s[72:73], s[6:7]
	s_cbranch_execz .LBB0_529
	s_waitcnt lgkmcnt(0)
	v_add_f32_e32 v142, v140, v141
	s_lshl_b32 s74, s19, 2
	v_lshlrev_b64 v[140:141], 8, v[146:147]
	s_ashr_i32 s75, s74, 31
	v_lshl_add_u64 v[140:141], s[26:27], 0, v[140:141]
	v_lshl_add_u64 v[140:141], s[74:75], 2, v[140:141]
	s_lshl_b32 s50, s37, 2
	v_lshl_add_u64 v[140:141], v[140:141], 0, s[50:51]
	global_store_dword v[140:141], v142, off
